# phase0a ada_tile: the eight weight-row loads of the next k-block are issued together one iteration ahead (software prefetch) instead of load-wait-use eight times
# speedup vs baseline: 1.0059x; 1.0048x over previous
; DI void ada_tile(const Params& p, int layer, int cg64, char* lds) {
;     ...
;   const int col = tid & 63, kq = tid >> 6;
;   const int n = cg64 * 64 + col;
;   const float* w = p.ada_w + (size_t)layer * 1024 * 6144 + n;
;   float acc[17];
; #pragma unroll
;   for (int i = 0; i < 17; ++i) acc[i] = 0.f;
; #pragma unroll 8
;   for (int kk = 0; kk < 256; ++kk) {
;     int k = kq * 256 + kk;
;     float wv = w[(size_t)k * 6144];
; #pragma unroll
;     for (int i = 0; i < 17; ++i) acc[i] += sc[i * 1024 + k] * wv;
.LBB0_35:
	s_or_b64 exec, exec, s[8:9]
	s_add_i32 s12, s33, 0xfffffd18
	s_cmpk_gt_u32 s12, 0x5f
	s_cselect_b64 s[8:9], -1, 0
	s_add_i32 s13, s33, 0xfffffcb8
	s_cmpk_lt_u32 s12, 0x60
	s_cselect_b32 s12, s12, s13
	s_and_b64 s[14:15], s[8:9], exec
	s_cselect_b32 s13, 0x1800000, 0
	v_ashrrev_i32_e32 v79, 6, v78
	v_and_b32_e32 v76, 63, v78
	v_mov_b32_e32 v74, s13
	v_lshlrev_b32_e32 v0, 8, v79
	s_movk_i32 s13, 0x6000
	v_lshl_or_b32 v80, s12, 6, v76
	v_mov_b32_e32 v81, v75
	v_mad_i64_i32 v[0:1], s[14:15], v0, s13, v[74:75]
	v_lshl_add_u64 v[0:1], v[80:81], 2, v[0:1]
	v_mov_b32_e32 v12, 0
	s_mov_b32 s12, 0
	v_lshl_add_u64 v[82:83], s[24:25], 0, v[0:1]
	s_mov_b32 s100, 0xfffd0000
	s_mov_b32 s101, -1
	v_lshl_add_u64 v[124:125], v[82:83], 0, s[100:101]
	s_mov_b32 s100, 0x6000
	s_mov_b32 s101, 0
	v_lshl_add_u64 v[124:125], v[124:125], 0, s[100:101]
	global_load_dword v126, v[124:125], off
	v_lshl_add_u64 v[124:125], v[124:125], 0, s[100:101]
	global_load_dword v127, v[124:125], off
	v_lshl_add_u64 v[124:125], v[124:125], 0, s[100:101]
	global_load_dword v128, v[124:125], off
	v_lshl_add_u64 v[124:125], v[124:125], 0, s[100:101]
	global_load_dword v129, v[124:125], off
	v_lshl_add_u64 v[124:125], v[124:125], 0, s[100:101]
	global_load_dword v130, v[124:125], off
	v_lshl_add_u64 v[124:125], v[124:125], 0, s[100:101]
	global_load_dword v131, v[124:125], off
	v_lshl_add_u64 v[124:125], v[124:125], 0, s[100:101]
	global_load_dword v132, v[124:125], off
	v_lshl_add_u64 v[124:125], v[124:125], 0, s[100:101]
	global_load_dword v133, v[124:125], off
	v_lshl_add_u32 v74, v79, 10, s88
	v_mov_b32_e32 v13, v12
	v_mov_b32_e32 v20, v12
	v_mov_b32_e32 v21, v12
	v_mov_b32_e32 v28, v12
	v_mov_b32_e32 v29, v12
	v_mov_b32_e32 v36, v12
	v_mov_b32_e32 v37, v12
	v_mov_b32_e32 v44, v12
	v_mov_b32_e32 v45, v12
	v_mov_b32_e32 v52, v12
	v_mov_b32_e32 v53, v12
	v_mov_b32_e32 v60, v12
	v_mov_b32_e32 v61, v12
	v_mov_b32_e32 v68, v12
	v_mov_b32_e32 v69, v12
	v_mov_b32_e32 v81, v12
	s_waitcnt lgkmcnt(0)
	s_barrier
.LBB0_36:
	s_waitcnt vmcnt(0)
	v_mov_b32_e32 v116, v126
	v_mov_b32_e32 v117, v127
	v_mov_b32_e32 v118, v128
	v_mov_b32_e32 v119, v129
	v_mov_b32_e32 v120, v130
	v_mov_b32_e32 v121, v131
	v_mov_b32_e32 v122, v132
	v_mov_b32_e32 v123, v133
	s_cmpk_eq_i32 s12, 0x3e0
	s_cbranch_scc1 .Lada_nopf
	v_lshl_add_u64 v[124:125], v[82:83], 0, s[100:101]
	global_load_dword v126, v[124:125], off
	v_lshl_add_u64 v[124:125], v[124:125], 0, s[100:101]
	global_load_dword v127, v[124:125], off
	v_lshl_add_u64 v[124:125], v[124:125], 0, s[100:101]
	global_load_dword v128, v[124:125], off
	v_lshl_add_u64 v[124:125], v[124:125], 0, s[100:101]
	global_load_dword v129, v[124:125], off
	v_lshl_add_u64 v[124:125], v[124:125], 0, s[100:101]
	global_load_dword v130, v[124:125], off
	v_lshl_add_u64 v[124:125], v[124:125], 0, s[100:101]
	global_load_dword v131, v[124:125], off
	v_lshl_add_u64 v[124:125], v[124:125], 0, s[100:101]
	global_load_dword v132, v[124:125], off
	v_lshl_add_u64 v[124:125], v[124:125], 0, s[100:101]
	global_load_dword v133, v[124:125], off
.Lada_nopf:
	s_mov_b32 s13, 0xfffd6000
	v_add_u32_e32 v96, s12, v74
	s_nop 0
	ds_read_b128 v[4:7], v96
	ds_read_b128 v[0:3], v96 offset:16
	ds_read_b128 v[8:11], v96 offset:4096
	s_mov_b32 s13, 0xfffdc000
	s_mov_b64 s[14:15], 0x30000
	s_waitcnt lgkmcnt(2)
	v_mov_b32_e32 v14, v4
	v_add_u32_e32 v4, 0x10000, v96
	s_waitcnt lgkmcnt(0)
	v_mov_b32_e32 v15, v8
	v_mov_b32_e32 v8, v5
	s_add_i32 s12, s12, 32
	s_cmpk_eq_i32 s12, 0x400
	v_mov_b32_e32 v98, v116
	v_pk_fma_f32 v[100:101], v[98:99], v[14:15], v[12:13] op_sel_hi:[0,1,1]
	ds_read_b128 v[12:15], v96 offset:8192
	ds_read_b128 v[16:19], v96 offset:12288
	s_waitcnt lgkmcnt(1)
	v_mov_b32_e32 v22, v12
	s_waitcnt lgkmcnt(0)
	v_mov_b32_e32 v23, v16
	v_pk_fma_f32 v[102:103], v[98:99], v[22:23], v[20:21] op_sel_hi:[0,1,1]
	ds_read_b128 v[20:23], v96 offset:16384
	ds_read_b128 v[24:27], v96 offset:20480
	v_mov_b32_e32 v16, v13
	s_waitcnt lgkmcnt(1)
	v_mov_b32_e32 v30, v20
	s_waitcnt lgkmcnt(0)
	v_mov_b32_e32 v31, v24
	v_pk_fma_f32 v[104:105], v[98:99], v[30:31], v[28:29] op_sel_hi:[0,1,1]
	ds_read_b128 v[28:31], v96 offset:24576
	ds_read_b128 v[32:35], v96 offset:28672
	v_mov_b32_e32 v24, v21
	s_waitcnt lgkmcnt(1)
	v_mov_b32_e32 v38, v28
	s_waitcnt lgkmcnt(0)
	v_mov_b32_e32 v39, v32
	v_pk_fma_f32 v[106:107], v[98:99], v[38:39], v[36:37] op_sel_hi:[0,1,1]
	ds_read_b128 v[36:39], v96 offset:32768
	ds_read_b128 v[40:43], v96 offset:36864
	v_mov_b32_e32 v32, v29
	s_waitcnt lgkmcnt(1)
	v_mov_b32_e32 v46, v36
	s_waitcnt lgkmcnt(0)
	v_mov_b32_e32 v47, v40
	v_pk_fma_f32 v[108:109], v[98:99], v[46:47], v[44:45] op_sel_hi:[0,1,1]
	ds_read_b128 v[44:47], v96 offset:40960
	ds_read_b128 v[48:51], v96 offset:45056
	v_mov_b32_e32 v40, v37
	s_waitcnt lgkmcnt(1)
	v_mov_b32_e32 v54, v44
	s_waitcnt lgkmcnt(0)
	v_mov_b32_e32 v55, v48
	v_pk_fma_f32 v[110:111], v[98:99], v[54:55], v[52:53] op_sel_hi:[0,1,1]
	ds_read_b128 v[52:55], v96 offset:49152
	ds_read_b128 v[56:59], v96 offset:53248
	v_mov_b32_e32 v48, v45
	s_waitcnt lgkmcnt(1)
	v_mov_b32_e32 v62, v52
	s_waitcnt lgkmcnt(0)
	v_mov_b32_e32 v63, v56
	v_pk_fma_f32 v[112:113], v[98:99], v[62:63], v[60:61] op_sel_hi:[0,1,1]
	ds_read_b128 v[60:63], v96 offset:57344
	ds_read_b128 v[64:67], v96 offset:61440
	v_mov_b32_e32 v56, v53
	s_waitcnt lgkmcnt(1)
	v_mov_b32_e32 v70, v60
	s_waitcnt lgkmcnt(0)
	v_mov_b32_e32 v71, v64
	v_pk_fma_f32 v[114:115], v[98:99], v[70:71], v[68:69] op_sel_hi:[0,1,1]
	ds_read_b128 v[68:71], v4
	v_mov_b32_e32 v64, v61
	s_waitcnt lgkmcnt(0)
; DI void ada_tile(const Params& p, int layer, int cg64, char* lds) {
;     ...
; #pragma unroll 8
;   for (int kk = 0; kk < 256; ++kk) {
;     int k = kq * 256 + kk;
;     float wv = w[(size_t)k * 6144];
; #pragma unroll
;     for (int i = 0; i < 17; ++i) acc[i] += sc[i * 1024 + k] * wv;
	v_fmac_f32_e32 v81, v98, v68
	s_mov_b32 s13, 0xfffe2000
	s_nop 0
	v_mov_b32_e32 v4, v117
	v_pk_fma_f32 v[8:9], v[4:5], v[8:9], v[100:101] op_sel_hi:[0,1,1]
	v_pk_fma_f32 v[12:13], v[4:5], v[16:17], v[102:103] op_sel_hi:[0,1,1]
	v_pk_fma_f32 v[16:17], v[4:5], v[24:25], v[104:105] op_sel_hi:[0,1,1]
	v_pk_fma_f32 v[20:21], v[4:5], v[32:33], v[106:107] op_sel_hi:[0,1,1]
	v_pk_fma_f32 v[24:25], v[4:5], v[40:41], v[108:109] op_sel_hi:[0,1,1]
	v_pk_fma_f32 v[28:29], v[4:5], v[48:49], v[110:111] op_sel_hi:[0,1,1]
	v_pk_fma_f32 v[32:33], v[4:5], v[56:57], v[112:113] op_sel_hi:[0,1,1]
	v_pk_fma_f32 v[36:37], v[4:5], v[64:65], v[114:115] op_sel_hi:[0,1,1]
	v_fmac_f32_e32 v81, v4, v69
	v_mov_b32_e32 v40, v6
	s_nop 0
	v_mov_b32_e32 v41, v10
	s_mov_b32 s13, 0xfffe8000
	v_mov_b32_e32 v10, v7
	v_mov_b32_e32 v4, v118
	v_pk_fma_f32 v[8:9], v[4:5], v[40:41], v[8:9] op_sel_hi:[0,1,1]
	v_mov_b32_e32 v40, v14
	v_mov_b32_e32 v41, v18
	v_pk_fma_f32 v[12:13], v[4:5], v[40:41], v[12:13] op_sel_hi:[0,1,1]
	v_mov_b32_e32 v40, v22
	v_mov_b32_e32 v41, v26
	v_pk_fma_f32 v[16:17], v[4:5], v[40:41], v[16:17] op_sel_hi:[0,1,1]
	v_mov_b32_e32 v40, v30
	v_mov_b32_e32 v41, v34
	v_pk_fma_f32 v[20:21], v[4:5], v[40:41], v[20:21] op_sel_hi:[0,1,1]
	v_mov_b32_e32 v40, v38
	v_mov_b32_e32 v41, v42
	v_pk_fma_f32 v[24:25], v[4:5], v[40:41], v[24:25] op_sel_hi:[0,1,1]
	v_mov_b32_e32 v40, v46
	v_mov_b32_e32 v41, v50
	v_pk_fma_f32 v[28:29], v[4:5], v[40:41], v[28:29] op_sel_hi:[0,1,1]
	v_mov_b32_e32 v40, v54
	v_mov_b32_e32 v41, v58
	v_pk_fma_f32 v[32:33], v[4:5], v[40:41], v[32:33] op_sel_hi:[0,1,1]
	v_mov_b32_e32 v40, v62
	v_mov_b32_e32 v41, v66
	v_pk_fma_f32 v[36:37], v[4:5], v[40:41], v[36:37] op_sel_hi:[0,1,1]
	v_fmac_f32_e32 v81, v4, v70
	v_mov_b32_e32 v18, v15
	s_nop 0
	v_mov_b32_e32 v26, v23
	v_mov_b32_e32 v34, v31
	v_mov_b32_e32 v42, v39
	v_mov_b32_e32 v50, v47
	v_mov_b32_e32 v58, v55
	v_mov_b32_e32 v66, v63
	s_mov_b32 s13, 0xfffee000
	v_mov_b32_e32 v4, v119
	v_pk_fma_f32 v[8:9], v[4:5], v[10:11], v[8:9] op_sel_hi:[0,1,1]
	v_pk_fma_f32 v[18:19], v[4:5], v[18:19], v[12:13] op_sel_hi:[0,1,1]
	v_pk_fma_f32 v[26:27], v[4:5], v[26:27], v[16:17] op_sel_hi:[0,1,1]
	v_pk_fma_f32 v[34:35], v[4:5], v[34:35], v[20:21] op_sel_hi:[0,1,1]
	v_pk_fma_f32 v[40:41], v[4:5], v[42:43], v[24:25] op_sel_hi:[0,1,1]
	v_pk_fma_f32 v[48:49], v[4:5], v[50:51], v[28:29] op_sel_hi:[0,1,1]
	v_pk_fma_f32 v[56:57], v[4:5], v[58:59], v[32:33] op_sel_hi:[0,1,1]
	v_pk_fma_f32 v[64:65], v[4:5], v[66:67], v[36:37] op_sel_hi:[0,1,1]
	v_fmac_f32_e32 v81, v4, v71
	v_mov_b32_e32 v10, v0
	s_nop 0
	ds_read_b128 v[4:7], v96 offset:4112
	v_add_u32_e32 v0, 0x10010, v96
	s_mov_b32 s13, 0xffff4000
	s_waitcnt lgkmcnt(0)
	v_mov_b32_e32 v11, v4
	v_mov_b32_e32 v4, v1
	v_mov_b32_e32 v68, v120
	v_pk_fma_f32 v[70:71], v[68:69], v[10:11], v[8:9] op_sel_hi:[0,1,1]
	ds_read_b128 v[8:11], v96 offset:8208
	ds_read_b128 v[12:15], v96 offset:12304
	s_waitcnt lgkmcnt(1)
	v_mov_b32_e32 v16, v8
	s_waitcnt lgkmcnt(0)
	v_mov_b32_e32 v17, v12
	v_pk_fma_f32 v[98:99], v[68:69], v[16:17], v[18:19] op_sel_hi:[0,1,1]
	ds_read_b128 v[16:19], v96 offset:16400
	ds_read_b128 v[20:23], v96 offset:20496
	v_mov_b32_e32 v12, v9
	s_waitcnt lgkmcnt(1)
	v_mov_b32_e32 v24, v16
	s_waitcnt lgkmcnt(0)
	v_mov_b32_e32 v25, v20
	v_pk_fma_f32 v[100:101], v[68:69], v[24:25], v[26:27] op_sel_hi:[0,1,1]
	ds_read_b128 v[24:27], v96 offset:24592
	ds_read_b128 v[28:31], v96 offset:28688
	v_mov_b32_e32 v20, v17
	s_waitcnt lgkmcnt(1)
	v_mov_b32_e32 v32, v24
	s_waitcnt lgkmcnt(0)
	v_mov_b32_e32 v33, v28
	v_pk_fma_f32 v[102:103], v[68:69], v[32:33], v[34:35] op_sel_hi:[0,1,1]
	ds_read_b128 v[32:35], v96 offset:32784
	ds_read_b128 v[36:39], v96 offset:36880
	v_mov_b32_e32 v28, v25
	s_waitcnt lgkmcnt(1)
	v_mov_b32_e32 v42, v32
	s_waitcnt lgkmcnt(0)
	v_mov_b32_e32 v43, v36
	v_pk_fma_f32 v[104:105], v[68:69], v[42:43], v[40:41] op_sel_hi:[0,1,1]
	ds_read_b128 v[40:43], v96 offset:40976
	ds_read_b128 v[44:47], v96 offset:45072
	v_mov_b32_e32 v36, v33
	s_waitcnt lgkmcnt(1)
	v_mov_b32_e32 v50, v40
	s_waitcnt lgkmcnt(0)
; DI void ada_tile(const Params& p, int layer, int cg64, char* lds) {
;     ...
; #pragma unroll 8
;   for (int kk = 0; kk < 256; ++kk) {
;     int k = kq * 256 + kk;
;     float wv = w[(size_t)k * 6144];
; #pragma unroll
;     for (int i = 0; i < 17; ++i) acc[i] += sc[i * 1024 + k] * wv;
;   }
;   __syncthreads();
;   float* red = (float*)lds;
; #pragma unroll
;   for (int i = 0; i < 17; ++i) red[(kq * 17 + i) * 64 + col] = acc[i];
;   __syncthreads();
;   float* mod = (float*)(p.ws + O_MOD) + (size_t)layer * 17 * 6144;
;   for (int e = tid; e < 17 * 64; e += 256) {
;     int bi = e >> 6, cc = e & 63;
;     float s = red[(0 * 17 + bi) * 64 + cc] + red[(1 * 17 + bi) * 64 + cc] + red[(2 * 17 + bi) * 64 + cc] +
;               red[(3 * 17 + bi) * 64 + cc];
;     int nn = cg64 * 64 + cc;
;     mod[bi * 6144 + nn] = s + p.ada_b[layer * 6144 + nn];
	v_mov_b32_e32 v51, v44
	v_pk_fma_f32 v[106:107], v[68:69], v[50:51], v[48:49] op_sel_hi:[0,1,1]
	ds_read_b128 v[48:51], v96 offset:49168
	ds_read_b128 v[52:55], v96 offset:53264
	v_mov_b32_e32 v44, v41
	s_waitcnt lgkmcnt(1)
	v_mov_b32_e32 v58, v48
	s_waitcnt lgkmcnt(0)
	v_mov_b32_e32 v59, v52
	v_pk_fma_f32 v[108:109], v[68:69], v[58:59], v[56:57] op_sel_hi:[0,1,1]
	ds_read_b128 v[56:59], v96 offset:57360
	ds_read_b128 v[60:63], v96 offset:61456
	v_mov_b32_e32 v52, v49
	s_waitcnt lgkmcnt(1)
	v_mov_b32_e32 v66, v56
	s_waitcnt lgkmcnt(0)
	v_mov_b32_e32 v67, v60
	v_pk_fma_f32 v[110:111], v[68:69], v[66:67], v[64:65] op_sel_hi:[0,1,1]
	ds_read_b128 v[64:67], v0
	v_mov_b32_e32 v60, v57
	s_waitcnt lgkmcnt(0)
	v_fmac_f32_e32 v81, v68, v64
	s_movk_i32 s13, 0xa000
	s_nop 0
	v_mov_b32_e32 v0, v121
	v_pk_fma_f32 v[4:5], v[0:1], v[4:5], v[70:71] op_sel_hi:[0,1,1]
	v_pk_fma_f32 v[8:9], v[0:1], v[12:13], v[98:99] op_sel_hi:[0,1,1]
	v_pk_fma_f32 v[12:13], v[0:1], v[20:21], v[100:101] op_sel_hi:[0,1,1]
	v_pk_fma_f32 v[16:17], v[0:1], v[28:29], v[102:103] op_sel_hi:[0,1,1]
	v_pk_fma_f32 v[20:21], v[0:1], v[36:37], v[104:105] op_sel_hi:[0,1,1]
	v_pk_fma_f32 v[24:25], v[0:1], v[44:45], v[106:107] op_sel_hi:[0,1,1]
	v_pk_fma_f32 v[28:29], v[0:1], v[52:53], v[108:109] op_sel_hi:[0,1,1]
	v_pk_fma_f32 v[32:33], v[0:1], v[60:61], v[110:111] op_sel_hi:[0,1,1]
	v_fmac_f32_e32 v81, v0, v65
	v_mov_b32_e32 v36, v2
	s_nop 0
	v_mov_b32_e32 v37, v6
	v_mov_b32_e32 v6, v3
	v_mov_b32_e32 v0, v122
	v_pk_fma_f32 v[4:5], v[0:1], v[36:37], v[4:5] op_sel_hi:[0,1,1]
	v_mov_b32_e32 v36, v10
	v_mov_b32_e32 v37, v14
	v_pk_fma_f32 v[8:9], v[0:1], v[36:37], v[8:9] op_sel_hi:[0,1,1]
	v_mov_b32_e32 v36, v18
	v_mov_b32_e32 v37, v22
	v_pk_fma_f32 v[36:37], v[0:1], v[36:37], v[12:13] op_sel_hi:[0,1,1]
	v_mov_b32_e32 v12, v26
	v_mov_b32_e32 v13, v30
	v_pk_fma_f32 v[16:17], v[0:1], v[12:13], v[16:17] op_sel_hi:[0,1,1]
	v_mov_b32_e32 v12, v34
	v_mov_b32_e32 v13, v38
	v_pk_fma_f32 v[40:41], v[0:1], v[12:13], v[20:21] op_sel_hi:[0,1,1]
	v_mov_b32_e32 v12, v42
	v_mov_b32_e32 v13, v46
	v_pk_fma_f32 v[24:25], v[0:1], v[12:13], v[24:25] op_sel_hi:[0,1,1]
	v_mov_b32_e32 v12, v50
	v_mov_b32_e32 v13, v54
	v_pk_fma_f32 v[48:49], v[0:1], v[12:13], v[28:29] op_sel_hi:[0,1,1]
	v_mov_b32_e32 v12, v58
	v_mov_b32_e32 v13, v62
	v_pk_fma_f32 v[32:33], v[0:1], v[12:13], v[32:33] op_sel_hi:[0,1,1]
	v_fmac_f32_e32 v81, v0, v66
	v_mov_b32_e32 v14, v11
	v_mov_b32_e32 v22, v19
	v_mov_b32_e32 v30, v27
	v_mov_b32_e32 v38, v35
	v_mov_b32_e32 v46, v43
	v_mov_b32_e32 v54, v51
	v_mov_b32_e32 v62, v59
	v_lshl_add_u64 v[82:83], v[82:83], 0, s[14:15]
	v_mov_b32_e32 v0, v123
	v_pk_fma_f32 v[12:13], v[0:1], v[6:7], v[4:5] op_sel_hi:[0,1,1]
	v_pk_fma_f32 v[20:21], v[0:1], v[14:15], v[8:9] op_sel_hi:[0,1,1]
	v_pk_fma_f32 v[28:29], v[0:1], v[22:23], v[36:37] op_sel_hi:[0,1,1]
	v_pk_fma_f32 v[36:37], v[0:1], v[30:31], v[16:17] op_sel_hi:[0,1,1]
	v_pk_fma_f32 v[44:45], v[0:1], v[38:39], v[40:41] op_sel_hi:[0,1,1]
	v_pk_fma_f32 v[52:53], v[0:1], v[46:47], v[24:25] op_sel_hi:[0,1,1]
	v_pk_fma_f32 v[60:61], v[0:1], v[54:55], v[48:49] op_sel_hi:[0,1,1]
	v_pk_fma_f32 v[68:69], v[0:1], v[62:63], v[32:33] op_sel_hi:[0,1,1]
	v_fmac_f32_e32 v81, v0, v67
	s_cbranch_scc0 .LBB0_36
	s_movk_i32 s12, 0x1100
	v_mul_lo_u32 v0, v79, s12
	v_lshlrev_b32_e32 v1, 2, v76
	s_movk_i32 s12, 0x440
	v_add3_u32 v0, s88, v0, v1
	v_cmp_gt_i32_e32 vcc, s12, v78
	s_barrier
	ds_write2st64_b32 v0, v12, v13 offset1:1
	ds_write2st64_b32 v0, v20, v21 offset0:2 offset1:3
	ds_write2st64_b32 v0, v28, v29 offset0:4 offset1:5
	ds_write2st64_b32 v0, v36, v37 offset0:6 offset1:7
	ds_write2st64_b32 v0, v44, v45 offset0:8 offset1:9
	ds_write2st64_b32 v0, v52, v53 offset0:10 offset1:11
	ds_write2st64_b32 v0, v60, v61 offset0:12 offset1:13
	ds_write2st64_b32 v0, v68, v69 offset0:14 offset1:15
	ds_write_b32 v0, v81 offset:4096
	s_waitcnt lgkmcnt(0)
	s_barrier
	s_and_saveexec_b64 s[12:13], vcc
	s_cbranch_execz .LBB0_40
	s_and_b64 s[14:15], s[8:9], exec
	s_cselect_b32 s14, 0x66000, 0
	s_add_u32 s14, s43, s14
	s_addc_u32 s15, s44, 0
	s_and_b64 s[8:9], s[8:9], exec
	s_cselect_b32 s8, 0x1800, 0
	v_add_u32_e32 v74, s8, v80
	v_lshl_add_u64 v[0:1], v[74:75], 2, s[58:59]
	v_lshl_add_u32 v2, v76, 2, s88
	s_mov_b64 s[8:9], 0
